# r1 chunk-KV units use the same unit-to-workgroup map as r2, so each chunk KV is produced on the XCD that later reads it
# speedup vs baseline: 1.0147x; 1.0147x over previous
.LBB0_129:
	s_or_b64 exec, exec, s[8:9]
	v_readlane_b32 s4, v251, 27
	v_readlane_b32 s5, v251, 28
	s_andn2_b64 vcc, exec, s[4:5]
	s_mov_b32 s12, s62
	s_cmpk_gt_i32 s12, 0x7f
	s_cbranch_scc1 .Lr1map_lat
	s_and_b32 s4, s12, 7
	s_lshl_b32 s4, s4, 1
	s_bfe_u32 s5, s12, 0x10003
	s_andn2_b32 s12, s12, 15
	s_or_b32 s12, s12, s4
	s_or_b32 s12, s12, s5
	s_branch .Lr1map_done
.Lr1map_lat:
	s_and_b32 s4, s12, 7
	s_lshl_b32 s4, s4, 3
	s_bfe_u32 s5, s12, 0x30003
	s_andn2_b32 s12, s12, 63
	s_or_b32 s12, s12, s4
	s_or_b32 s12, s12, s5
.Lr1map_done:
	s_cbranch_vccz .LBB0_163
